# attention body top: the wait for the previous body's output-store acknowledgements removed (it guards nothing the next loads need; later counted waits only get stricter)
# baseline (speedup 1.0000x reference)
; #define LAS __attribute__((address_space(3)))
; __device__ __forceinline__ void phase4_attn(const Args& a, LAS unsigned char* lds) {
;     ...
;                 const int bh = b * 2 + hkv, head = hkv * 4 + g;
;                 int tid = tid0; asm volatile("" : "+v"(tid));
;                 const int lane = tid & 63, r = lane & 31, h = lane >> 5, ql = 32 * half + r, pos = 64 * t + ql, tok = b * 2048 + pos;
;                 comb[hkv][0] = zero16(); comb[hkv][1] = zero16();
;                 const float g0 = gates[(size_t)tok * 24 + head * 3 + 0], g1 = gates[(size_t)tok * 24 + head * 3 + 1], g2 = gates[(size_t)tok * 24 + head * 3 + 2];
;                 __syncthreads();
;                 {
;                     const bf16_t* kc = kcmp + (size_t)bh * 128 * 64; const bf16_t* vc = vcmpT + (size_t)bh * 64 * 128;
; #pragma unroll
;                     for (int i = 0; i < 2; ++i) { const int c = tid + 512 * i;
;                         const u32x4 kv = *(const u32x4*)(kc + (size_t)c * 8);
;                         *(LAS u32x4*)(lds + A_CMPK + (c >> 3) * A_KSTR + (c & 7) * 16) = kv;
;                         const u32x4 vv = *(const u32x4*)(vc + (size_t)c * 8);
;                         LAS unsigned char* vp = lds + A_CMPV + (c >> 4) * A_CVSTR + (c & 15) * 16;
;                         *(LAS u32x2*)vp = (u32x2){vv.x, vv.y}; *(LAS u32x2*)(vp + 8) = (u32x2){vv.z, vv.w}; }
;                 }
;                 bf16x8_t qf[4];
; #pragma unroll
;                 for (int ks = 0; ks < 4; ++ks) qf[ks] = __builtin_nontemporal_load((const bf16x8_t*)(qn + (size_t)tok * 512 + head * 64 + 16 * ks + 8 * h));
;                 __syncthreads();
.LBB0_715:
	s_and_b64 s[0:1], s[64:65], exec
	v_readlane_b32 s0, v254, 29
	v_readlane_b32 s1, v254, 30
	v_mov_b32_e32 v152, v184
	s_cselect_b32 s38, s0, s1
	s_lshl_b32 s24, s38, 6
	v_and_b32_e32 v100, 31, v152
	v_or_b32_e32 v98, s79, v100
	v_or_b32_e32 v154, s24, v98
	v_or_b32_e32 v4, s39, v154
	v_mad_i64_i32 v[0:1], s[4:5], v4, s83, v[116:117]
	global_load_dwordx3 v[112:114], v[0:1], off
	v_lshlrev_b32_e32 v0, 4, v152
	v_ashrrev_i32_e32 v153, 31, v152
	v_readlane_b32 s6, v254, 39
	v_and_b32_e32 v1, 0x70, v0
	v_and_b32_e32 v0, 0xf0, v0
	v_lshlrev_b64 v[10:11], 4, v[152:153]
	v_readlane_b32 s7, v254, 40
	v_add_u32_e32 v6, s85, v1
	v_add_u32_e32 v8, s86, v0
	v_lshl_add_u64 v[0:1], s[6:7], 0, v[10:11]
	s_waitcnt lgkmcnt(0)
	s_barrier
	v_readlane_b32 s8, v254, 31
	v_readlane_b32 s9, v254, 32
	global_load_dwordx4 v[16:19], v[0:1], off
	v_add_u32_e32 v14, 0x200, v152
	v_ashrrev_i32_e32 v15, 31, v14
	v_lshlrev_b64 v[12:13], 4, v[14:15]
	v_lshl_add_u64 v[36:37], s[8:9], 0, v[10:11]
	global_load_dwordx4 v[20:23], v[36:37], off
	v_lshl_add_u64 v[36:37], s[6:7], 0, v[12:13]
	global_load_dwordx4 v[24:27], v[36:37], off
	v_lshl_add_u64 v[36:37], s[8:9], 0, v[12:13]
	global_load_dwordx4 v[28:31], v[36:37], off
	v_readlane_b32 s4, v254, 24
	v_readlane_b32 s5, v254, 25
	v_ashrrev_i32_e32 v5, 31, v4
	v_bfe_u32 v101, v152, 5, 1
	v_lshlrev_b64 v[72:73], 10, v[4:5]
	v_lshlrev_b32_e32 v118, 4, v101
	v_lshl_add_u64 v[0:1], s[4:5], 0, v[72:73]
	v_lshl_add_u64 v[4:5], v[0:1], 0, v[118:119]
	global_load_dwordx4 v[0:3], v[4:5], off nt
	global_load_dwordx4 v[74:77], v[4:5], off offset:32 nt
	global_load_dwordx4 v[68:71], v[4:5], off offset:64 nt
	global_load_dwordx4 v[64:67], v[4:5], off offset:96 nt
	v_ashrrev_i32_e32 v99, 3, v152
	v_ashrrev_i32_e32 v7, 4, v152
	v_mul_u32_u24_e32 v153, 0x90, v100
	v_add3_u32 v82, s85, v118, v153
	v_mad_u32_u24 v32, v99, s87, v6
	v_mad_u32_u24 v33, v7, s94, v8
	v_add_u32_e32 v35, 0x2100, v33
	s_cmp_gt_u32 s38, 15
	s_cselect_b64 s[0:1], -1, 0
	s_cmp_lt_u32 s38, 16
	s_mov_b64 s[2:3], -1
	s_cselect_b64 s[62:63], -1, 0
	s_waitcnt vmcnt(7)
	ds_write_b128 v32, v[16:19]
	s_waitcnt vmcnt(6)
	ds_write2_b64 v33, v[20:21], v[22:23] offset1:1
	s_waitcnt vmcnt(5)
	ds_write_b128 v32, v[24:27] offset:9216
	s_waitcnt vmcnt(4)
	ds_write2_b64 v35, v[28:29], v[30:31] offset1:1
	s_waitcnt lgkmcnt(0)
	s_barrier
	s_waitcnt vmcnt(0)
	v_mov_b32_e32 v84, v0
	v_mov_b32_e32 v85, v1
	v_mov_b32_e32 v86, v2
	v_mov_b32_e32 v87, v3
	v_lshlrev_b32_e32 v155, 2, v101
	v_lshlrev_b32_e32 v156, 3, v101
	v_mul_u32_u24_e32 v157, 0x108, v100
	v_add3_u32 v244, s86, v156, v157
	v_add_u32_e32 v245, 0x2000, v244
	v_lshlrev_b32_e32 v239, 4, v155
	v_sub_u32_e32 v236, v154, v239
	v_subrev_u32_e32 v236, 31, v236
	v_ashrrev_i32_e32 v236, 4, v236
	v_cmp_lt_i32_e32 vcc, v185, v188
	s_nop 1
	v_cndmask_b32_e32 v239, v115, v185, vcc
	v_lshlrev_b32_e32 v193, 2, v239
	v_mov_b32_e32 v0, 0
	v_mov_b32_e32 v1, 0
	v_mov_b32_e32 v2, 0
	v_mov_b32_e32 v3, 0
	v_mov_b32_e32 v4, 0
	v_mov_b32_e32 v5, 0
	v_mov_b32_e32 v6, 0
	v_mov_b32_e32 v7, 0
	v_mov_b32_e32 v8, 0
	v_mov_b32_e32 v9, 0
	v_mov_b32_e32 v10, 0
	v_mov_b32_e32 v11, 0
	v_mov_b32_e32 v12, 0
	v_mov_b32_e32 v13, 0
	v_mov_b32_e32 v14, 0
	v_mov_b32_e32 v15, 0
	v_mov_b32_e32 v16, 0
	v_mov_b32_e32 v17, 0
	v_mov_b32_e32 v18, 0
	v_mov_b32_e32 v19, 0
	v_mov_b32_e32 v20, 0
	v_mov_b32_e32 v21, 0
	v_mov_b32_e32 v22, 0
	v_mov_b32_e32 v23, 0
	v_mov_b32_e32 v24, 0
	v_mov_b32_e32 v25, 0
	v_mov_b32_e32 v26, 0
	v_mov_b32_e32 v27, 0
	v_mov_b32_e32 v28, 0
	v_mov_b32_e32 v29, 0
	v_mov_b32_e32 v30, 0
	v_mov_b32_e32 v31, 0
	v_mov_b32_e32 v160, 0
	v_mov_b32_e32 v161, 0
	v_mov_b32_e32 v162, 0
	v_mov_b32_e32 v163, 0
	v_mov_b32_e32 v164, 0
	v_mov_b32_e32 v165, 0
	v_mov_b32_e32 v166, 0
	v_mov_b32_e32 v167, 0
	v_mov_b32_e32 v168, 0
	v_mov_b32_e32 v169, 0
	v_mov_b32_e32 v170, 0
	v_mov_b32_e32 v171, 0
	v_mov_b32_e32 v172, 0
	v_mov_b32_e32 v173, 0
	v_mov_b32_e32 v174, 0
	v_mov_b32_e32 v175, 0
	v_mov_b32_e32 v176, 0
	v_mov_b32_e32 v177, 0
	v_mov_b32_e32 v178, 0
	v_mov_b32_e32 v179, 0
	v_mov_b32_e32 v180, 0
	v_mov_b32_e32 v181, 0
	v_mov_b32_e32 v182, 0
	v_mov_b32_e32 v183, 0
	v_mov_b32_e32 v246, 0
	v_mov_b32_e32 v247, 0
	v_mov_b32_e32 v248, 0
	v_mov_b32_e32 v249, 0
	v_mov_b32_e32 v250, 0
	v_mov_b32_e32 v251, 0
	v_mov_b32_e32 v252, 0
	v_mov_b32_e32 v253, 0
	v_readfirstlane_b32 s7, v152
	s_bfe_u32 s7, s7, 0x10006
	s_lshl_b32 s9, s38, 1
	s_add_i32 s7, s7, s9
	s_lshr_b32 s7, s7, 4
	s_cmp_eq_u32 s7, 0
	s_cbranch_scc1 .Lc0_n1
	s_cmp_eq_u32 s7, 1
	s_cbranch_scc1 .Lc0_n2
	s_cmp_eq_u32 s7, 2
	s_cbranch_scc1 .Lc0_n3
	s_branch .Lc0_n4
